# sg_core small GEMM K-steps: 6 fragment ds_reads issued together into distinct VGPRs with counted lgkmcnt (sg_out, sg_branch) on top of P8 rebalance
# baseline (speedup 1.0000x reference)
; DEV f32x4 mfma32(bf16x8 a, bf16x8 b, f32x4 c) { return __builtin_amdgcn_mfma_f32_16x16x32_bf16(a, b, c, 0, 0, 0); }
; template <int R>
; DEV void sg_core(const bf16_t* __restrict__ A, int lda, const bf16_t* __restrict__ Bt, int ldb, int K, int row0, int col0, f32x4 (&acc)[2], unsigned char* smem) {
;     ...
;     for (int u = 0; u < R; ++u) {
;       const int kt = kt0 + u;
;       unsigned char* cur = smem + (u & 1) * 18432;
;       unsigned char* nxt = smem + ((u + 1) & 1) * 18432;
;       if (kt + 1 < nt) { *(u32x4*)(nxt + woff) = ra[(u + 1) % R]; *(u32x4*)(nxt + 9216 + woff) = rb[(u + 1) % R]; }
;       if (kt + R < nt) { ra[u] = *(const u32x4*)(pa + (size_t)(kt + R) * 64); rb[u] = *(const u32x4*)(pb + (size_t)(kt + R) * 64); }
; #pragma unroll
;       for (int ks = 0; ks < 2; ++ks) {
;         const bf16x8 af = *(const bf16x8*)(cur + aoff + ks * 64);
; #pragma unroll
;         for (int ni = 0; ni < 2; ++ni) {
;           const bf16x8 bfr = *(const bf16x8*)(cur + boff + ni * 16 * 144 + ks * 64);
;           acc[ni] = mfma32(bfr, af, acc[ni]);
;         }
;       }
;       asm volatile("s_waitcnt lgkmcnt(0)\n\ts_barrier" ::: "memory");
;     }
.LBB0_114:
	ds_read_b128 v[184:187], v177
	ds_read_b128 v[188:191], v179 offset:9216
	ds_read_b128 v[192:195], v179 offset:11520
	ds_read_b128 v[196:199], v177 offset:64
	ds_read_b128 v[220:223], v179 offset:9280
	ds_read_b128 v[224:227], v179 offset:11584
	s_and_b64 vcc, exec, s[38:39]
	s_waitcnt lgkmcnt(4)
	v_mfma_f32_16x16x32_bf16 v[160:163], v[188:191], v[184:187], v[160:163]
	s_waitcnt lgkmcnt(3)
	v_mfma_f32_16x16x32_bf16 v[164:167], v[192:195], v[184:187], v[164:167]
	s_waitcnt lgkmcnt(1)
	v_mfma_f32_16x16x32_bf16 v[160:163], v[220:223], v[196:199], v[160:163]
	s_waitcnt lgkmcnt(0)
	v_mfma_f32_16x16x32_bf16 v[164:167], v[224:227], v[196:199], v[164:167]
	s_waitcnt lgkmcnt(0)
	s_barrier
	s_cbranch_vccnz .LBB0_99
	global_load_dwordx4 v[152:155], v[180:181], off offset:1920
	global_load_dwordx4 v[156:159], v[182:183], off offset:1920
	ds_write_b128 v168, v[96:99]
	ds_write_b128 v168, v[116:119] offset:9216
	s_branch .LBB0_99

; DEV f32x4 mfma32(bf16x8 a, bf16x8 b, f32x4 c) { return __builtin_amdgcn_mfma_f32_16x16x32_bf16(a, b, c, 0, 0, 0); }
; template <int R>
; DEV void sg_core(const bf16_t* __restrict__ A, int lda, const bf16_t* __restrict__ Bt, int ldb, int K, int row0, int col0, f32x4 (&acc)[2], unsigned char* smem) {
;     ...
;     for (int u = 0; u < R; ++u) {
;       const int kt = kt0 + u;
;       unsigned char* cur = smem + (u & 1) * 18432;
;       unsigned char* nxt = smem + ((u + 1) & 1) * 18432;
;       if (kt + 1 < nt) { *(u32x4*)(nxt + woff) = ra[(u + 1) % R]; *(u32x4*)(nxt + 9216 + woff) = rb[(u + 1) % R]; }
;       if (kt + R < nt) { ra[u] = *(const u32x4*)(pa + (size_t)(kt + R) * 64); rb[u] = *(const u32x4*)(pb + (size_t)(kt + R) * 64); }
; #pragma unroll
;       for (int ks = 0; ks < 2; ++ks) {
;         const bf16x8 af = *(const bf16x8*)(cur + aoff + ks * 64);
; #pragma unroll
;         for (int ni = 0; ni < 2; ++ni) {
;           const bf16x8 bfr = *(const bf16x8*)(cur + boff + ni * 16 * 144 + ks * 64);
;           acc[ni] = mfma32(bfr, af, acc[ni]);
;         }
;       }
;       asm volatile("s_waitcnt lgkmcnt(0)\n\ts_barrier" ::: "memory");
;     }
.LBB0_256:
	ds_read_b128 v[80:83], v77 offset:18432
	ds_read_b128 v[84:87], v78 offset:27648
	ds_read_b128 v[88:91], v78 offset:29952
	ds_read_b128 v[92:95], v77 offset:18496
	ds_read_b128 v[96:99], v78 offset:27712
	ds_read_b128 v[100:103], v78 offset:30016
	s_mov_b64 s[8:9], 0
	s_andn2_b64 vcc, exec, s[4:5]
	s_waitcnt lgkmcnt(4)
	v_mfma_f32_16x16x32_bf16 v[64:67], v[84:87], v[80:83], v[64:67]
	s_waitcnt lgkmcnt(3)
	v_mfma_f32_16x16x32_bf16 v[68:71], v[88:91], v[80:83], v[68:71]
	s_waitcnt lgkmcnt(1)
	v_mfma_f32_16x16x32_bf16 v[64:67], v[96:99], v[92:95], v[64:67]
	s_waitcnt lgkmcnt(0)
	v_mfma_f32_16x16x32_bf16 v[68:71], v[100:103], v[92:95], v[68:71]
	s_waitcnt lgkmcnt(0)
	s_barrier
	s_cbranch_vccz .LBB0_254

; DEV f32x4 mfma32(bf16x8 a, bf16x8 b, f32x4 c) { return __builtin_amdgcn_mfma_f32_16x16x32_bf16(a, b, c, 0, 0, 0); }
; template <int R>
; DEV void sg_core(const bf16_t* __restrict__ A, int lda, const bf16_t* __restrict__ Bt, int ldb, int K, int row0, int col0, f32x4 (&acc)[2], unsigned char* smem) {
;     ...
;     for (int u = 0; u < R; ++u) {
;       const int kt = kt0 + u;
;       unsigned char* cur = smem + (u & 1) * 18432;
;       unsigned char* nxt = smem + ((u + 1) & 1) * 18432;
;       if (kt + 1 < nt) { *(u32x4*)(nxt + woff) = ra[(u + 1) % R]; *(u32x4*)(nxt + 9216 + woff) = rb[(u + 1) % R]; }
;       if (kt + R < nt) { ra[u] = *(const u32x4*)(pa + (size_t)(kt + R) * 64); rb[u] = *(const u32x4*)(pb + (size_t)(kt + R) * 64); }
; #pragma unroll
;       for (int ks = 0; ks < 2; ++ks) {
;         const bf16x8 af = *(const bf16x8*)(cur + aoff + ks * 64);
; #pragma unroll
;         for (int ni = 0; ni < 2; ++ni) {
;           const bf16x8 bfr = *(const bf16x8*)(cur + boff + ni * 16 * 144 + ks * 64);
;           acc[ni] = mfma32(bfr, af, acc[ni]);
;         }
;       }
;       asm volatile("s_waitcnt lgkmcnt(0)\n\ts_barrier" ::: "memory");
;     }
.LBB0_259:
	ds_read_b128 v[80:83], v77
	ds_read_b128 v[84:87], v78 offset:9216
	ds_read_b128 v[88:91], v78 offset:11520
	ds_read_b128 v[92:95], v77 offset:64
	ds_read_b128 v[96:99], v78 offset:9280
	ds_read_b128 v[100:103], v78 offset:11584
	v_cndmask_b32_e64 v79, 0, 1, s[8:9]
	v_cmp_ne_u32_e64 s[38:39], 1, v79
	s_andn2_b64 vcc, exec, s[8:9]
	s_waitcnt lgkmcnt(4)
	v_mfma_f32_16x16x32_bf16 v[64:67], v[84:87], v[80:83], v[64:67]
	s_waitcnt lgkmcnt(3)
	v_mfma_f32_16x16x32_bf16 v[68:71], v[88:91], v[80:83], v[68:71]
	s_waitcnt lgkmcnt(1)
	v_mfma_f32_16x16x32_bf16 v[64:67], v[96:99], v[92:95], v[64:67]
	s_waitcnt lgkmcnt(0)
	v_mfma_f32_16x16x32_bf16 v[68:71], v[100:103], v[92:95], v[68:71]
	s_waitcnt lgkmcnt(0)
	s_barrier
	ds_write_b128 v76, v[12:15]
	ds_write_b128 v76, v[16:19] offset:9216
	s_cbranch_vccnz .LBB0_261
	global_load_dwordx4 v[4:7], v[72:73], off offset:1152
	global_load_dwordx4 v[8:11], v[74:75], off offset:1152
.LBB0_261:
	ds_read_b128 v[80:83], v77 offset:18432
	ds_read_b128 v[84:87], v78 offset:27648
	ds_read_b128 v[88:91], v78 offset:29952
	ds_read_b128 v[92:95], v77 offset:18496
	ds_read_b128 v[96:99], v78 offset:27712
	ds_read_b128 v[100:103], v78 offset:30016
	s_and_b64 vcc, exec, s[38:39]
	s_waitcnt lgkmcnt(4)
	v_mfma_f32_16x16x32_bf16 v[64:67], v[84:87], v[80:83], v[64:67]
	s_waitcnt lgkmcnt(3)
	v_mfma_f32_16x16x32_bf16 v[68:71], v[88:91], v[80:83], v[68:71]
	s_waitcnt lgkmcnt(1)
	v_mfma_f32_16x16x32_bf16 v[64:67], v[96:99], v[92:95], v[64:67]
	s_waitcnt lgkmcnt(0)
	v_mfma_f32_16x16x32_bf16 v[68:71], v[100:103], v[92:95], v[68:71]
	s_waitcnt lgkmcnt(0)
	s_barrier
	ds_write_b128 v76, v[24:27] offset:18432
	ds_write_b128 v76, v[28:31] offset:27648
	s_cbranch_vccnz .LBB0_263
	global_load_dwordx4 v[12:15], v[72:73], off offset:1280
	global_load_dwordx4 v[16:19], v[74:75], off offset:1280
.LBB0_263:
	ds_read_b128 v[80:83], v77
	ds_read_b128 v[84:87], v78 offset:9216
	ds_read_b128 v[88:91], v78 offset:11520
	ds_read_b128 v[92:95], v77 offset:64
	ds_read_b128 v[96:99], v78 offset:9280
	ds_read_b128 v[100:103], v78 offset:11584
	s_and_b64 vcc, exec, s[38:39]
	s_waitcnt lgkmcnt(4)
	v_mfma_f32_16x16x32_bf16 v[64:67], v[84:87], v[80:83], v[64:67]
	s_waitcnt lgkmcnt(3)
	v_mfma_f32_16x16x32_bf16 v[68:71], v[88:91], v[80:83], v[68:71]
	s_waitcnt lgkmcnt(1)
	v_mfma_f32_16x16x32_bf16 v[64:67], v[96:99], v[92:95], v[64:67]
	s_waitcnt lgkmcnt(0)
	v_mfma_f32_16x16x32_bf16 v[68:71], v[100:103], v[92:95], v[68:71]
	s_waitcnt lgkmcnt(0)
	s_barrier
	ds_write_b128 v76, v[32:35]
	ds_write_b128 v76, v[36:39] offset:9216
	s_cbranch_vccnz .LBB0_265
	global_load_dwordx4 v[24:27], v[72:73], off offset:1408
	global_load_dwordx4 v[28:31], v[74:75], off offset:1408
.LBB0_265:
	ds_read_b128 v[80:83], v77 offset:18432
	ds_read_b128 v[84:87], v78 offset:27648
	ds_read_b128 v[88:91], v78 offset:29952
	ds_read_b128 v[92:95], v77 offset:18496
	ds_read_b128 v[96:99], v78 offset:27712
	ds_read_b128 v[100:103], v78 offset:30016
	s_and_b64 vcc, exec, s[38:39]
	s_waitcnt lgkmcnt(4)
	v_mfma_f32_16x16x32_bf16 v[64:67], v[84:87], v[80:83], v[64:67]
	s_waitcnt lgkmcnt(3)
	v_mfma_f32_16x16x32_bf16 v[68:71], v[88:91], v[80:83], v[68:71]
	s_waitcnt lgkmcnt(1)
	v_mfma_f32_16x16x32_bf16 v[64:67], v[96:99], v[92:95], v[64:67]
	s_waitcnt lgkmcnt(0)
	v_mfma_f32_16x16x32_bf16 v[68:71], v[100:103], v[92:95], v[68:71]
	s_waitcnt lgkmcnt(0)
	s_barrier
	ds_write_b128 v76, v[40:43] offset:18432
	ds_write_b128 v76, v[44:47] offset:27648
	s_cbranch_vccnz .LBB0_267
	global_load_dwordx4 v[32:35], v[72:73], off offset:1536
	global_load_dwordx4 v[36:39], v[74:75], off offset:1536
.LBB0_267:
	ds_read_b128 v[80:83], v77
	ds_read_b128 v[84:87], v78 offset:9216
	ds_read_b128 v[88:91], v78 offset:11520
	ds_read_b128 v[92:95], v77 offset:64
	ds_read_b128 v[96:99], v78 offset:9280
	ds_read_b128 v[100:103], v78 offset:11584
	s_and_b64 vcc, exec, s[38:39]
	s_waitcnt lgkmcnt(4)
	v_mfma_f32_16x16x32_bf16 v[64:67], v[84:87], v[80:83], v[64:67]
	s_waitcnt lgkmcnt(3)
	v_mfma_f32_16x16x32_bf16 v[68:71], v[88:91], v[80:83], v[68:71]
	s_waitcnt lgkmcnt(1)
	v_mfma_f32_16x16x32_bf16 v[64:67], v[96:99], v[92:95], v[64:67]
	s_waitcnt lgkmcnt(0)
	v_mfma_f32_16x16x32_bf16 v[68:71], v[100:103], v[92:95], v[68:71]
	s_waitcnt lgkmcnt(0)
	s_barrier
	ds_write_b128 v76, v[48:51]
	ds_write_b128 v76, v[52:55] offset:9216
	s_cbranch_vccnz .LBB0_269
	global_load_dwordx4 v[40:43], v[72:73], off offset:1664
	global_load_dwordx4 v[44:47], v[74:75], off offset:1664
.LBB0_269:
	ds_read_b128 v[80:83], v77 offset:18432
	ds_read_b128 v[84:87], v78 offset:27648
	ds_read_b128 v[88:91], v78 offset:29952
	ds_read_b128 v[92:95], v77 offset:18496
	ds_read_b128 v[96:99], v78 offset:27712
	ds_read_b128 v[100:103], v78 offset:30016
	s_and_b64 vcc, exec, s[38:39]
	s_waitcnt lgkmcnt(4)
	v_mfma_f32_16x16x32_bf16 v[64:67], v[84:87], v[80:83], v[64:67]
	s_waitcnt lgkmcnt(3)
	v_mfma_f32_16x16x32_bf16 v[68:71], v[88:91], v[80:83], v[68:71]
	s_waitcnt lgkmcnt(1)
	v_mfma_f32_16x16x32_bf16 v[64:67], v[96:99], v[92:95], v[64:67]
	s_waitcnt lgkmcnt(0)
	v_mfma_f32_16x16x32_bf16 v[68:71], v[100:103], v[92:95], v[68:71]
	s_waitcnt lgkmcnt(0)
	s_barrier
	ds_write_b128 v76, v[56:59] offset:18432
	ds_write_b128 v76, v[60:63] offset:27648
	s_cbranch_vccnz .LBB0_271
	global_load_dwordx4 v[48:51], v[72:73], off offset:1792
	global_load_dwordx4 v[52:55], v[74:75], off offset:1792
.LBB0_271:
	ds_read_b128 v[80:83], v77
	ds_read_b128 v[84:87], v78 offset:9216
	ds_read_b128 v[88:91], v78 offset:11520
	ds_read_b128 v[92:95], v77 offset:64
	ds_read_b128 v[96:99], v78 offset:9280
	ds_read_b128 v[100:103], v78 offset:11584
	s_and_b64 vcc, exec, s[38:39]
	s_waitcnt lgkmcnt(4)
	v_mfma_f32_16x16x32_bf16 v[64:67], v[84:87], v[80:83], v[64:67]
	s_waitcnt lgkmcnt(3)
	v_mfma_f32_16x16x32_bf16 v[68:71], v[88:91], v[80:83], v[68:71]
	s_waitcnt lgkmcnt(1)
	v_mfma_f32_16x16x32_bf16 v[64:67], v[96:99], v[92:95], v[64:67]
	s_waitcnt lgkmcnt(0)
	v_mfma_f32_16x16x32_bf16 v[68:71], v[100:103], v[92:95], v[68:71]
	s_waitcnt lgkmcnt(0)
	s_barrier
	s_cbranch_vccnz .LBB0_256
	global_load_dwordx4 v[56:59], v[72:73], off offset:1920
	global_load_dwordx4 v[60:63], v[74:75], off offset:1920
	s_waitcnt vmcnt(3)
	ds_write_b128 v76, v[0:3]
	s_waitcnt vmcnt(2)
	ds_write_b128 v76, v[20:23] offset:9216
	s_branch .LBB0_256

; DEV int tidx() { int t = threadIdx.x; asm volatile("" : "+v"(t)); return t; }
; DEV f32x4 mfma32(bf16x8 a, bf16x8 b, f32x4 c) { return __builtin_amdgcn_mfma_f32_16x16x32_bf16(a, b, c, 0, 0, 0); }
; template <int R>
; DEV void sg_core(const bf16_t* __restrict__ A, int lda, const bf16_t* __restrict__ Bt, int ldb, int K, int row0, int col0, f32x4 (&acc)[2], unsigned char* smem) {
;   const int tid = tidx(), lane = tid & 63, wid = tid >> 6, wr = wid >> 1, wc = wid & 1, fr = lane & 15, fq = lane >> 4;
;   const int crow = tid >> 3, ckc = tid & 7;
;   const bf16_t* pa = A + (size_t)(row0 + crow) * lda + ckc * 8;
;   const bf16_t* pb = Bt + (size_t)(col0 + crow) * ldb + ckc * 8;
;   const int nt = K >> 6;
;   const int woff = crow * 144 + ckc * 16;
;   u32x4 ra[R], rb[R];
; #pragma unroll
;   for (int j = 0; j < R; ++j) { ra[j] = *(const u32x4*)(pa + j * 64); rb[j] = *(const u32x4*)(pb + j * 64); }
;   *(u32x4*)(smem + woff) = ra[0]; *(u32x4*)(smem + 9216 + woff) = rb[0];
;   asm volatile("s_waitcnt lgkmcnt(0)\n\ts_barrier" ::: "memory");
;   const int aoff = (wr * 16 + fr) * 144 + fq * 16, boff = 9216 + (wc * 32 + fr) * 144 + fq * 16;
; #pragma unroll 1
;   for (int kt0 = 0; kt0 < nt; kt0 += R) {
; #pragma unroll
;     for (int u = 0; u < R; ++u) {
;       const int kt = kt0 + u;
;       unsigned char* cur = smem + (u & 1) * 18432;
;       unsigned char* nxt = smem + ((u + 1) & 1) * 18432;
;       if (kt + 1 < nt) { *(u32x4*)(nxt + woff) = ra[(u + 1) % R]; *(u32x4*)(nxt + 9216 + woff) = rb[(u + 1) % R]; }
;       if (kt + R < nt) { ra[u] = *(const u32x4*)(pa + (size_t)(kt + R) * 64); rb[u] = *(const u32x4*)(pb + (size_t)(kt + R) * 64); }
; #pragma unroll
;       for (int ks = 0; ks < 2; ++ks) {
;         const bf16x8 af = *(const bf16x8*)(cur + aoff + ks * 64);
; #pragma unroll
;         for (int ni = 0; ni < 2; ++ni) {
;           const bf16x8 bfr = *(const bf16x8*)(cur + boff + ni * 16 * 144 + ks * 64);
;           acc[ni] = mfma32(bfr, af, acc[ni]);
;         }
;       }
;       asm volatile("s_waitcnt lgkmcnt(0)\n\ts_barrier" ::: "memory");
;     }
.LBB0_299:
	s_cmp_eq_u32 s4, 0x100000
	s_cselect_b32 s6, 0x600, s75
	s_cmp_lg_u32 s4, 0
	s_cselect_b32 s6, s6, 0x400
	s_lshl_b32 s6, s6, 1
	s_add_u32 s12, s15, s6
	v_mov_b32_e32 v74, v171
	s_addc_u32 s13, s16, 0
	v_mov_b64_e32 v[8:9], s[12:13]
	v_ashrrev_i32_e32 v72, 3, v74
	v_add_u32_e32 v10, s35, v72
	v_mad_i64_i32 v[8:9], s[12:13], v10, s95, v[8:9]
	v_lshlrev_b32_e32 v10, 4, v74
	v_and_b32_e32 v168, 0x70, v10
	v_ashrrev_i32_e32 v73, 31, v72
	v_lshl_add_u64 v[64:65], v[8:9], 0, v[168:169]
	v_lshlrev_b64 v[8:9], 10, v[72:73]
	s_add_u32 s12, s21, s4
	v_or_b32_e32 v8, v8, v168
	s_addc_u32 s13, s34, s5
	v_lshl_add_u64 v[12:13], s[12:13], 0, v[8:9]
	global_load_dwordx4 v[8:11], v[64:65], off
	s_mov_b32 s6, 0xd80000
	v_add_co_u32_e32 v68, vcc, s6, v12
	v_mul_lo_u32 v76, v72, s33
	s_nop 0
	v_addc_co_u32_e32 v69, vcc, 0, v13, vcc
	global_load_dwordx4 v[12:15], v[68:69], off
	global_load_dwordx4 v[16:19], v[64:65], off offset:128
	global_load_dwordx4 v[20:23], v[68:69], off offset:128
	global_load_dwordx4 v[24:27], v[64:65], off offset:256
	global_load_dwordx4 v[28:31], v[68:69], off offset:256
	global_load_dwordx4 v[32:35], v[64:65], off offset:384
	global_load_dwordx4 v[36:39], v[68:69], off offset:384
	global_load_dwordx4 v[40:43], v[64:65], off offset:512
	global_load_dwordx4 v[44:47], v[68:69], off offset:512
	global_load_dwordx4 v[48:51], v[64:65], off offset:640
	global_load_dwordx4 v[52:55], v[68:69], off offset:640
	global_load_dwordx4 v[56:59], v[64:65], off offset:768
	global_load_dwordx4 v[60:63], v[68:69], off offset:768
	s_nop 0
	global_load_dwordx4 v[64:67], v[64:65], off offset:896
	s_nop 0
	global_load_dwordx4 v[68:71], v[68:69], off offset:896
	v_and_b32_e32 v75, 15, v74
	v_add3_u32 v76, v76, v168, 0
	v_and_b32_e32 v73, 48, v74
	s_cmp_eq_u32 s4, 0x200000
	s_cselect_b64 s[12:13], -1, 0
	s_waitcnt vmcnt(0)
	ds_write_b128 v76, v[8:11]
	ds_write_b128 v76, v[12:15] offset:9216
	v_and_or_b32 v8, v72, s40, v75
	v_lshrrev_b32_e32 v9, 1, v74
	v_mul_lo_u32 v8, v8, s33
	v_and_or_b32 v9, v9, 32, v75
	s_waitcnt lgkmcnt(0)
	s_barrier
	v_mul_u32_u24_e32 v9, 0x90, v9
	v_add3_u32 v72, 0, v8, v73
	ds_write_b128 v76, v[16:19] offset:18432
	ds_write_b128 v76, v[20:23] offset:27648
	v_add3_u32 v73, 0, v9, v73
	ds_read_b128 v[8:11], v72
	ds_read_b128 v[12:15], v73 offset:9216
	ds_read_b128 v[80:83], v73 offset:11520
	ds_read_b128 v[84:87], v72 offset:64
	ds_read_b128 v[88:91], v73 offset:9280
	ds_read_b128 v[92:95], v73 offset:11584
	s_waitcnt lgkmcnt(4)
	v_mfma_f32_16x16x32_bf16 v[4:7], v[12:15], v[8:11], v[4:7]
	s_waitcnt lgkmcnt(3)
	v_mfma_f32_16x16x32_bf16 v[0:3], v[80:83], v[8:11], v[0:3]
	s_waitcnt lgkmcnt(1)
	v_mfma_f32_16x16x32_bf16 v[4:7], v[88:91], v[84:87], v[4:7]
	s_waitcnt lgkmcnt(0)
	v_mfma_f32_16x16x32_bf16 v[0:3], v[92:95], v[84:87], v[0:3]
	s_waitcnt lgkmcnt(0)
	s_barrier
	ds_write_b128 v76, v[24:27]
	ds_write_b128 v76, v[28:31] offset:9216
	ds_read_b128 v[8:11], v72 offset:18432
	ds_read_b128 v[12:15], v73 offset:27648
	ds_read_b128 v[80:83], v73 offset:29952
	ds_read_b128 v[84:87], v72 offset:18496
	ds_read_b128 v[88:91], v73 offset:27712
	ds_read_b128 v[92:95], v73 offset:30016
	s_waitcnt lgkmcnt(4)
	v_mfma_f32_16x16x32_bf16 v[4:7], v[12:15], v[8:11], v[4:7]
	s_waitcnt lgkmcnt(3)
	v_mfma_f32_16x16x32_bf16 v[0:3], v[80:83], v[8:11], v[0:3]
	s_waitcnt lgkmcnt(1)
	v_mfma_f32_16x16x32_bf16 v[4:7], v[88:91], v[84:87], v[4:7]
	s_waitcnt lgkmcnt(0)
	v_mfma_f32_16x16x32_bf16 v[0:3], v[92:95], v[84:87], v[0:3]
	s_waitcnt lgkmcnt(0)
	s_barrier
	ds_write_b128 v76, v[32:35] offset:18432
	ds_write_b128 v76, v[36:39] offset:27648
	ds_read_b128 v[8:11], v72
	ds_read_b128 v[12:15], v73 offset:9216
	ds_read_b128 v[80:83], v73 offset:11520
	ds_read_b128 v[84:87], v72 offset:64
	ds_read_b128 v[88:91], v73 offset:9280
	ds_read_b128 v[92:95], v73 offset:11584
	s_waitcnt lgkmcnt(4)
	v_mfma_f32_16x16x32_bf16 v[4:7], v[12:15], v[8:11], v[4:7]
	s_waitcnt lgkmcnt(3)
	v_mfma_f32_16x16x32_bf16 v[0:3], v[80:83], v[8:11], v[0:3]
	s_waitcnt lgkmcnt(1)
	v_mfma_f32_16x16x32_bf16 v[4:7], v[88:91], v[84:87], v[4:7]
	s_waitcnt lgkmcnt(0)
	v_mfma_f32_16x16x32_bf16 v[0:3], v[92:95], v[84:87], v[0:3]
	s_waitcnt lgkmcnt(0)
	s_barrier
	ds_write_b128 v76, v[40:43]
	ds_write_b128 v76, v[44:47] offset:9216
	ds_read_b128 v[8:11], v72 offset:18432
	ds_read_b128 v[12:15], v73 offset:27648
	ds_read_b128 v[80:83], v73 offset:29952
	ds_read_b128 v[84:87], v72 offset:18496
	ds_read_b128 v[88:91], v73 offset:27712
	ds_read_b128 v[92:95], v73 offset:30016
	s_waitcnt lgkmcnt(4)
	v_mfma_f32_16x16x32_bf16 v[4:7], v[12:15], v[8:11], v[4:7]
	s_waitcnt lgkmcnt(3)
	v_mfma_f32_16x16x32_bf16 v[0:3], v[80:83], v[8:11], v[0:3]
	s_waitcnt lgkmcnt(1)
	v_mfma_f32_16x16x32_bf16 v[4:7], v[88:91], v[84:87], v[4:7]
	s_waitcnt lgkmcnt(0)
	v_mfma_f32_16x16x32_bf16 v[0:3], v[92:95], v[84:87], v[0:3]
	s_waitcnt lgkmcnt(0)
	s_barrier
	ds_write_b128 v76, v[48:51] offset:18432
	ds_write_b128 v76, v[52:55] offset:27648
	ds_read_b128 v[8:11], v72
	ds_read_b128 v[12:15], v73 offset:9216
	ds_read_b128 v[80:83], v73 offset:11520
	ds_read_b128 v[84:87], v72 offset:64
	ds_read_b128 v[88:91], v73 offset:9280
	ds_read_b128 v[92:95], v73 offset:11584
	s_waitcnt lgkmcnt(4)
	v_mfma_f32_16x16x32_bf16 v[4:7], v[12:15], v[8:11], v[4:7]
	s_waitcnt lgkmcnt(3)
	v_mfma_f32_16x16x32_bf16 v[0:3], v[80:83], v[8:11], v[0:3]
	s_waitcnt lgkmcnt(1)
	v_mfma_f32_16x16x32_bf16 v[4:7], v[88:91], v[84:87], v[4:7]
	s_waitcnt lgkmcnt(0)
	v_mfma_f32_16x16x32_bf16 v[0:3], v[92:95], v[84:87], v[0:3]
	s_waitcnt lgkmcnt(0)
	s_barrier
; DEV f32x4 mfma32(bf16x8 a, bf16x8 b, f32x4 c) { return __builtin_amdgcn_mfma_f32_16x16x32_bf16(a, b, c, 0, 0, 0); }
; template <int R>
; DEV void sg_core(const bf16_t* __restrict__ A, int lda, const bf16_t* __restrict__ Bt, int ldb, int K, int row0, int col0, f32x4 (&acc)[2], unsigned char* smem) {
;     ...
;     for (int u = 0; u < R; ++u) {
;       const int kt = kt0 + u;
;       unsigned char* cur = smem + (u & 1) * 18432;
;       unsigned char* nxt = smem + ((u + 1) & 1) * 18432;
;       if (kt + 1 < nt) { *(u32x4*)(nxt + woff) = ra[(u + 1) % R]; *(u32x4*)(nxt + 9216 + woff) = rb[(u + 1) % R]; }
;       if (kt + R < nt) { ra[u] = *(const u32x4*)(pa + (size_t)(kt + R) * 64); rb[u] = *(const u32x4*)(pb + (size_t)(kt + R) * 64); }
; #pragma unroll
;       for (int ks = 0; ks < 2; ++ks) {
;         const bf16x8 af = *(const bf16x8*)(cur + aoff + ks * 64);
; #pragma unroll
;         for (int ni = 0; ni < 2; ++ni) {
;           const bf16x8 bfr = *(const bf16x8*)(cur + boff + ni * 16 * 144 + ks * 64);
;           acc[ni] = mfma32(bfr, af, acc[ni]);
;         }
;       }
;       asm volatile("s_waitcnt lgkmcnt(0)\n\ts_barrier" ::: "memory");
;     }
	ds_write_b128 v76, v[56:59]
	ds_write_b128 v76, v[60:63] offset:9216
	ds_read_b128 v[8:11], v72 offset:18432
	ds_read_b128 v[12:15], v73 offset:27648
	ds_read_b128 v[80:83], v73 offset:29952
	ds_read_b128 v[84:87], v72 offset:18496
	ds_read_b128 v[88:91], v73 offset:27712
	ds_read_b128 v[92:95], v73 offset:30016
	s_waitcnt lgkmcnt(4)
	v_mfma_f32_16x16x32_bf16 v[4:7], v[12:15], v[8:11], v[4:7]
	s_waitcnt lgkmcnt(3)
	v_mfma_f32_16x16x32_bf16 v[0:3], v[80:83], v[8:11], v[0:3]
	s_waitcnt lgkmcnt(1)
	v_mfma_f32_16x16x32_bf16 v[4:7], v[88:91], v[84:87], v[4:7]
	s_waitcnt lgkmcnt(0)
	v_mfma_f32_16x16x32_bf16 v[0:3], v[92:95], v[84:87], v[0:3]
	s_waitcnt lgkmcnt(0)
	s_barrier
	ds_write_b128 v76, v[64:67] offset:18432
	ds_write_b128 v76, v[68:71] offset:27648
	ds_read_b128 v[8:11], v72
	ds_read_b128 v[12:15], v73 offset:9216
	ds_read_b128 v[80:83], v73 offset:11520
	ds_read_b128 v[84:87], v72 offset:64
	ds_read_b128 v[88:91], v73 offset:9280
	ds_read_b128 v[92:95], v73 offset:11584
	s_waitcnt lgkmcnt(4)
	v_mfma_f32_16x16x32_bf16 v[4:7], v[12:15], v[8:11], v[4:7]
	s_waitcnt lgkmcnt(3)
	v_mfma_f32_16x16x32_bf16 v[0:3], v[80:83], v[8:11], v[0:3]
	s_waitcnt lgkmcnt(1)
	v_mfma_f32_16x16x32_bf16 v[4:7], v[88:91], v[84:87], v[4:7]
	s_waitcnt lgkmcnt(0)
	v_mfma_f32_16x16x32_bf16 v[0:3], v[92:95], v[84:87], v[0:3]
	s_waitcnt lgkmcnt(0)
	s_barrier
	ds_read_b128 v[8:11], v72 offset:18432
	ds_read_b128 v[12:15], v73 offset:27648
	ds_read_b128 v[80:83], v73 offset:29952
	ds_read_b128 v[84:87], v72 offset:18496
	ds_read_b128 v[88:91], v73 offset:27712
	ds_read_b128 v[92:95], v73 offset:30016
	s_waitcnt lgkmcnt(4)
	v_mfma_f32_16x16x32_bf16 v[4:7], v[12:15], v[8:11], v[4:7]
	s_waitcnt lgkmcnt(3)
	v_mfma_f32_16x16x32_bf16 v[0:3], v[80:83], v[8:11], v[0:3]
	s_waitcnt lgkmcnt(1)
	v_mfma_f32_16x16x32_bf16 v[4:7], v[88:91], v[84:87], v[4:7]
	s_waitcnt lgkmcnt(0)
	v_mfma_f32_16x16x32_bf16 v[0:3], v[92:95], v[84:87], v[0:3]
	s_waitcnt lgkmcnt(0)
	s_barrier
; DEV unsigned cvt_pk_bf16(float lo, float hi) { const f32x2_ v = {lo, hi}; return __builtin_bit_cast(unsigned, __builtin_convertvector(v, bf16x2n_)); }
; DEV float bflo(unsigned w) { return __uint_as_float(w << 16); }
; DEV float bfhi(unsigned w) { return __uint_as_float(w & 0xffff0000u); }
; DEV void sg_branch(const Params& p, unsigned char* smem) {
;     ...
;     for (int s = 0; s < 3; ++s) {
;       const int aoff = (s == 0) ? RG : (s == 1 ? AQ : CB);
;       sg_core<8>(Z + (size_t)TP * NIN + aoff, NIN, W + (size_t)s * D * 512, 512, 512, row0, col0, acc, smem);
;       const int sb = s == 2 ? 2 : s + 1; const float one = s == 2 ? 0.f : 1.f;
;       SG_EPI({
;         const u32x2 ga = *(const u32x2*)(Z + row * NIN + GT + s * D + col), gb = *(const u32x2*)(Z + row * NIN + GT + sb * D + col);
;         acc[ni][0] *= (1.0f + one * __expf(-bflo(gb.x))) * __builtin_amdgcn_rcpf(1.0f + __expf(-bflo(ga.x)));
;         acc[ni][1] *= (1.0f + one * __expf(-bfhi(gb.x))) * __builtin_amdgcn_rcpf(1.0f + __expf(-bfhi(ga.x)));
;         acc[ni][2] *= (1.0f + one * __expf(-bflo(gb.y))) * __builtin_amdgcn_rcpf(1.0f + __expf(-bflo(ga.y)));
;         acc[ni][3] *= (1.0f + one * __expf(-bfhi(gb.y))) * __builtin_amdgcn_rcpf(1.0f + __expf(-bfhi(ga.y)));
;       })
;     }
;     SG_EPI({ u32x2 w; w.x = cvt_pk_bf16(acc[ni][0], acc[ni][1]); w.y = cvt_pk_bf16(acc[ni][2], acc[ni][3]); *(u32x2*)(H + row * D + col) = w; })
;   }
	v_mov_b32_e32 v9, v171
	v_mov_b32_e32 v14, v171
	v_mov_b32_e32 v13, s27
	v_ashrrev_i32_e32 v10, 3, v14
	v_and_b32_e32 v10, -16, v10
	v_and_b32_e32 v168, 15, v9
	v_ashrrev_i32_e32 v11, 31, v10
	v_or_b32_e32 v12, s26, v168
	v_lshrrev_b32_e32 v14, 1, v14
	v_lshl_add_u64 v[12:13], v[12:13], 0, v[10:11]
	v_and_b32_e32 v16, 32, v14
	v_lshrrev_b32_e32 v9, 2, v9
	v_mov_b64_e32 v[14:15], s[28:29]
	v_cndmask_b32_e64 v8, 1.0, 0, s[12:13]
	v_and_b32_e32 v9, 12, v9
	v_mad_u64_u32 v[14:15], s[38:39], v12, s95, v[14:15]
	s_and_b64 s[12:13], s[12:13], exec
	v_lshl_add_u64 v[10:11], s[2:3], 0, v[10:11]
	v_add_u32_e32 v12, s20, v16
	v_or3_b32 v17, v9, v16, s19
	v_mad_i32_i24 v15, v13, s95, v15
	s_cselect_b32 s6, 0x800, s36
	v_lshl_add_u64 v[10:11], v[10:11], 0, v[168:169]
	v_add_lshl_u32 v168, v12, v9, 1
	v_lshl_add_u64 v[14:15], s[6:7], 1, v[14:15]
	v_mad_u64_u32 v[12:13], s[12:13], v10, s95, v[168:169]
	v_lshlrev_b32_e32 v168, 1, v17
	v_lshl_add_u64 v[14:15], v[14:15], 0, v[168:169]
	s_mov_b64 s[12:13], 0x4701e00
	s_mov_b32 s6, 0x4701000
	v_lshl_add_u64 v[16:17], v[14:15], 0, s[12:13]
	v_add_co_u32_e32 v14, vcc, s6, v14
	v_mad_i32_i24 v13, v11, s95, v13
	s_nop 0
	v_addc_co_u32_e32 v15, vcc, 0, v15, vcc
	global_load_dwordx2 v[14:15], v[14:15], off offset:3584
	v_lshl_add_u64 v[10:11], s[8:9], 0, v[12:13]
	global_load_dwordx2 v[12:13], v[10:11], off
	s_add_u32 s4, s4, 0x100000
	s_addc_u32 s5, s5, 0
	s_add_u32 s8, s8, 0x800
	s_addc_u32 s9, s9, 0
	s_addk_i32 s36, 0x400
	s_cmp_eq_u32 s4, 0x300000
	s_waitcnt vmcnt(1)
	v_lshlrev_b32_e32 v9, 16, v14
	v_mul_f32_e32 v9, 0xbfb8aa3b, v9
	v_exp_f32_e32 v18, v9
	s_waitcnt vmcnt(0)
	v_lshlrev_b32_e32 v9, 16, v12
	v_mul_f32_e32 v9, 0xbfb8aa3b, v9
	v_exp_f32_e32 v9, v9
	s_nop 0
	v_add_f32_e32 v9, 1.0, v9
	v_rcp_f32_e32 v20, v9
	v_and_b32_e32 v9, 0xffff0000, v14
	v_mul_f32_e32 v9, 0xbfb8aa3b, v9
	v_exp_f32_e32 v19, v9
	v_and_b32_e32 v9, 0xffff0000, v12
	v_mul_f32_e32 v9, 0xbfb8aa3b, v9
	v_exp_f32_e32 v9, v9
	s_nop 0
	v_add_f32_e32 v9, 1.0, v9
	v_rcp_f32_e32 v21, v9
	v_pk_fma_f32 v[18:19], v[8:9], v[18:19], 1.0 op_sel_hi:[0,1,0]
	v_lshlrev_b32_e32 v9, 16, v15
	v_mul_f32_e32 v9, 0xbfb8aa3b, v9
	v_exp_f32_e32 v14, v9
	v_lshlrev_b32_e32 v9, 16, v13
	v_mul_f32_e32 v9, 0xbfb8aa3b, v9
	v_exp_f32_e32 v9, v9
	v_pk_mul_f32 v[18:19], v[20:21], v[18:19]
	v_add_f32_e32 v9, 1.0, v9
	v_rcp_f32_e32 v12, v9
	v_and_b32_e32 v9, 0xffff0000, v15
	v_mul_f32_e32 v9, 0xbfb8aa3b, v9
	v_exp_f32_e32 v15, v9
	v_and_b32_e32 v9, 0xffff0000, v13
	v_mul_f32_e32 v9, 0xbfb8aa3b, v9
	v_exp_f32_e32 v9, v9
	v_pk_mul_f32 v[4:5], v[4:5], v[18:19]
	v_add_f32_e32 v9, 1.0, v9
	v_rcp_f32_e32 v13, v9
	v_pk_fma_f32 v[14:15], v[8:9], v[14:15], 1.0 op_sel_hi:[0,1,0]
	v_pk_mul_f32 v[12:13], v[12:13], v[14:15]
	s_nop 0
	v_pk_mul_f32 v[6:7], v[6:7], v[12:13]
	global_load_dwordx2 v[10:11], v[10:11], off offset:32
	s_nop 0
	global_load_dwordx2 v[12:13], v[16:17], off offset:32
	s_waitcnt vmcnt(0)
	v_lshlrev_b32_e32 v9, 16, v12
	v_mul_f32_e32 v9, 0xbfb8aa3b, v9
	v_exp_f32_e32 v14, v9
	v_lshlrev_b32_e32 v9, 16, v10
	v_mul_f32_e32 v9, 0xbfb8aa3b, v9
	v_exp_f32_e32 v9, v9
	s_nop 0
	v_add_f32_e32 v9, 1.0, v9
	v_rcp_f32_e32 v16, v9
	v_and_b32_e32 v9, 0xffff0000, v12
	v_mul_f32_e32 v9, 0xbfb8aa3b, v9
	v_exp_f32_e32 v15, v9
	v_and_b32_e32 v9, 0xffff0000, v10
	v_mul_f32_e32 v9, 0xbfb8aa3b, v9
	v_exp_f32_e32 v9, v9
	s_nop 0
	v_add_f32_e32 v9, 1.0, v9
	v_rcp_f32_e32 v17, v9
	v_pk_fma_f32 v[14:15], v[8:9], v[14:15], 1.0 op_sel_hi:[0,1,0]
	v_lshlrev_b32_e32 v9, 16, v13
	v_mul_f32_e32 v9, 0xbfb8aa3b, v9
	v_exp_f32_e32 v12, v9
	v_lshlrev_b32_e32 v9, 16, v11
	v_mul_f32_e32 v9, 0xbfb8aa3b, v9
	v_exp_f32_e32 v9, v9
	v_pk_mul_f32 v[14:15], v[16:17], v[14:15]
	v_add_f32_e32 v9, 1.0, v9
	v_rcp_f32_e32 v10, v9
	v_and_b32_e32 v9, 0xffff0000, v13
	v_mul_f32_e32 v9, 0xbfb8aa3b, v9
	v_exp_f32_e32 v13, v9
	v_and_b32_e32 v9, 0xffff0000, v11
	v_mul_f32_e32 v9, 0xbfb8aa3b, v9
	v_exp_f32_e32 v9, v9
	v_pk_mul_f32 v[0:1], v[0:1], v[14:15]
	v_add_f32_e32 v9, 1.0, v9
	v_rcp_f32_e32 v11, v9
	v_pk_fma_f32 v[8:9], v[8:9], v[12:13], 1.0 op_sel_hi:[0,1,0]
	v_pk_mul_f32 v[8:9], v[10:11], v[8:9]
	s_nop 0
	v_pk_mul_f32 v[2:3], v[2:3], v[8:9]
	s_cbranch_scc0 .LBB0_299
	v_mov_b32_e32 v12, v171
	v_mov_b32_e32 v13, v171
	v_mov_b32_e32 v11, s27
	v_ashrrev_i32_e32 v8, 3, v13
	v_and_b32_e32 v8, -16, v8
	v_ashrrev_i32_e32 v9, 31, v8
	v_and_or_b32 v10, v12, 15, s26
	v_lshl_add_u64 v[8:9], v[10:11], 0, v[8:9]
	v_lshrrev_b32_e32 v10, 1, v13
	v_lshrrev_b32_e32 v11, 2, v12
	v_and_b32_e32 v10, 32, v10
	v_and_b32_e32 v11, 12, v11
	v_readlane_b32 s36, v248, 37
	v_readlane_b32 s2, v249, 52
	v_or3_b32 v10, v11, v10, s19
	v_lshlrev_b64 v[8:9], 11, v[8:9]
	v_readlane_b32 s38, v248, 39
	s_add_i32 s17, s17, s2
	v_readlane_b32 s2, v249, 33
	v_lshl_add_u64 v[8:9], s[24:25], 0, v[8:9]
	v_lshlrev_b32_e32 v168, 1, v10
	s_add_i32 s14, s14, s38
	s_add_i32 s18, s18, s2
	v_cvt_pk_bf16_f32 v4, v4, v5
	v_cvt_pk_bf16_f32 v5, v6, v7
	v_lshl_add_u64 v[6:7], v[8:9], 0, v[168:169]
	v_cvt_pk_bf16_f32 v0, v0, v1
	v_cvt_pk_bf16_f32 v1, v2, v3
	s_cmpk_gt_i32 s14, 0xff
	global_store_dwordx2 v[6:7], v[4:5], off
	v_readlane_b32 s37, v248, 38
	v_readlane_b32 s39, v248, 40
	global_store_dwordx2 v[6:7], v[0:1], off offset:32
	s_cbranch_scc0 .LBB0_298
